# attention units: waves 4-7 start the q-tile work s_sleep 24 later (stagger of SIMD partners that run the same program)
# speedup vs baseline: 1.0051x; 1.0009x over previous
.LBB0_413:
	s_or_b64 exec, exec, s[0:1]
	s_waitcnt vmcnt(0)
	v_cndmask_b32_e64 v35, 0, v80, s[28:29]
	v_cndmask_b32_e64 v37, 0, v78, s[28:29]
	v_cndmask_b32_e64 v34, 0, v81, s[28:29]
	v_cndmask_b32_e64 v36, 0, v79, s[28:29]
	ds_write_b16 v38, v37 offset:56960
	ds_write_b16_d16_hi v38, v37 offset:57432
	ds_write_b16 v38, v36 offset:57904
	ds_write_b16_d16_hi v38, v36 offset:58376
	ds_write_b16 v38, v35 offset:58848
	ds_write_b16_d16_hi v38, v35 offset:59320
	ds_write_b16 v38, v34 offset:59792
	ds_write_b16_d16_hi v38, v34 offset:60264
	s_cmp_lt_u32 s33, 2
	v_and_b32_e32 v35, 64, v211
	s_cselect_b64 vcc, -1, 0
	v_xor_b32_e32 v34, 16, v211
	v_add_u32_e32 v35, 64, v35
	v_cndmask_b32_e32 v74, 0, v197, vcc
	s_and_b64 s[0:1], vcc, exec
	v_cmp_lt_i32_e32 vcc, v34, v35
	s_cselect_b32 s0, 1, 31
	s_cmp_eq_u32 s33, 0
	v_cndmask_b32_e32 v34, v211, v34, vcc
	v_lshlrev_b32_e32 v113, 2, v34
	v_xor_b32_e32 v34, 32, v211
	s_cselect_b32 s1, s64, 0x1fe0
	v_cmp_lt_i32_e32 vcc, v34, v35
	s_bitcmp0_b32 s0, 1
	v_mov_b32_e32 v88, v74
	v_cndmask_b32_e32 v34, v211, v34, vcc
	s_cselect_b64 vcc, -1, 0
	s_bitcmp0_b32 s0, 2
	v_cndmask_b32_e32 v76, 0, v197, vcc
	s_cselect_b64 vcc, -1, 0
	s_bitcmp0_b32 s0, 3
	v_cndmask_b32_e32 v80, 0, v197, vcc
	s_cselect_b64 vcc, -1, 0
	s_bitcmp0_b32 s1, 5
	v_cndmask_b32_e32 v84, 0, v197, vcc
	s_cselect_b64 vcc, -1, 0
	s_bitcmp0_b32 s1, 6
	v_cndmask_b32_e32 v122, 0, v197, vcc
	s_cselect_b64 vcc, -1, 0
	s_bitcmp0_b32 s1, 7
	v_cndmask_b32_e32 v126, 0, v197, vcc
	s_cselect_b64 vcc, -1, 0
	s_bitcmp0_b32 s1, 8
	v_lshlrev_b32_e32 v115, 2, v34
	v_cndmask_b32_e32 v130, 0, v197, vcc
	s_cselect_b64 vcc, -1, 0
	v_xor_b32_e32 v34, 1, v211
	v_cndmask_b32_e32 v134, 0, v197, vcc
	v_cmp_lt_i32_e32 vcc, v34, v35
	v_mov_b32_e32 v78, v76
	v_mov_b32_e32 v79, v76
	v_cndmask_b32_e32 v34, v211, v34, vcc
	v_lshlrev_b32_e32 v117, 2, v34
	v_xor_b32_e32 v34, 2, v211
	v_cmp_lt_i32_e32 vcc, v34, v35
	v_mov_b32_e32 v82, v80
	v_mov_b32_e32 v83, v80
	v_cndmask_b32_e32 v34, v211, v34, vcc
	v_lshlrev_b32_e32 v119, 2, v34
	v_lshlrev_b64 v[34:35], 11, v[90:91]
	v_mov_b32_e32 v86, v84
	v_mov_b32_e32 v87, v84
	v_mov_b32_e32 v89, v74
	v_mov_b32_e32 v124, v122
	v_mov_b32_e32 v125, v122
	v_mov_b32_e32 v128, v126
	v_mov_b32_e32 v129, v126
	v_mov_b32_e32 v132, v130
	v_mov_b32_e32 v133, v130
	v_mov_b32_e32 v136, v134
	v_mov_b32_e32 v137, v134
	v_lshl_add_u64 v[138:139], v[104:105], 0, v[34:35]
	v_lshl_add_u64 v[140:141], v[106:107], 0, v[34:35]
	v_lshl_add_u64 v[142:143], v[108:109], 0, v[34:35]
	v_lshl_add_u64 v[144:145], v[110:111], 0, v[34:35]
	s_mov_b64 s[24:25], 0
	s_waitcnt lgkmcnt(0)
	s_barrier
	v_readfirstlane_b32 s0, v0
	s_nop 3
	s_cmp_lt_u32 s0, 0x100
	s_cbranch_scc1 .Lattn_stagger_done
	s_sleep 24
.Lattn_stagger_done:
.LBB0_414:
	v_add_u32_e32 v90, v187, v188
	ds_read_b128 v[34:37], v90
	ds_read_b128 v[38:41], v90 offset:64
	s_cmp_eq_u32 s24, 0
	s_cselect_b64 s[0:1], -1, 0
	v_cndmask_b32_e64 v53, v21, v5, s[0:1]
	v_cndmask_b32_e64 v52, v20, v4, s[0:1]
	v_cndmask_b32_e64 v51, v19, v3, s[0:1]
	v_cndmask_b32_e64 v50, v18, v2, s[0:1]
	v_cndmask_b32_e64 v149, v25, v9, s[0:1]
	v_cndmask_b32_e64 v148, v24, v8, s[0:1]
	s_waitcnt lgkmcnt(1)
	v_mfma_f32_16x16x32_bf16 v[34:37], v[34:37], v[50:53], 0
	v_cndmask_b32_e64 v147, v23, v7, s[0:1]
	v_cndmask_b32_e64 v146, v22, v6, s[0:1]
	global_load_dword v121, v[96:97], off
	ds_read_b128 v[42:45], v90 offset:39232
	s_waitcnt lgkmcnt(1)
	v_mfma_f32_16x16x32_bf16 v[150:153], v[38:41], v[146:149], v[34:37]
	ds_read_b128 v[38:41], v90 offset:4416
	ds_read_b128 v[46:49], v90 offset:43584
	ds_read_b128 v[202:205], v90 offset:47936
	ds_read_b128 v[34:37], v90 offset:4352
	s_waitcnt lgkmcnt(0)
	v_mfma_f32_16x16x32_bf16 v[34:37], v[34:37], v[50:53], 0
	s_waitcnt vmcnt(0)
	v_mul_f32_e32 v75, 0x3fb8aa3b, v121
	v_mfma_f32_16x16x32_bf16 v[154:157], v[38:41], v[146:149], v[34:37]
	ds_read_b128 v[38:41], v90 offset:8768
	s_nop 3
	ds_read_b128 v[34:37], v90 offset:8704
	s_waitcnt lgkmcnt(0)
	v_mfma_f32_16x16x32_bf16 v[34:37], v[34:37], v[50:53], 0
	v_mfma_f32_16x16x32_bf16 v[158:161], v[38:41], v[146:149], v[34:37]
	ds_read_b128 v[38:41], v90 offset:13120
	s_nop 5
	ds_read_b128 v[34:37], v90 offset:13056
	s_waitcnt lgkmcnt(0)
	v_mfma_f32_16x16x32_bf16 v[34:37], v[34:37], v[50:53], 0
	v_mfma_f32_16x16x32_bf16 v[70:73], v[38:41], v[146:149], v[34:37]
	ds_read_b128 v[38:41], v90 offset:17472
	s_nop 5
	ds_read_b128 v[34:37], v90 offset:17408
	s_waitcnt lgkmcnt(0)
	v_mfma_f32_16x16x32_bf16 v[34:37], v[34:37], v[50:53], 0
	v_add_f32_e64 v70, v86, v70
	v_add_f32_e64 v71, v87, v71
	v_mfma_f32_16x16x32_bf16 v[66:69], v[38:41], v[146:149], v[34:37]
	ds_read_b128 v[38:41], v90 offset:21824
	s_nop 3
	ds_read_b128 v[34:37], v90 offset:21760
	s_waitcnt lgkmcnt(0)
	v_mfma_f32_16x16x32_bf16 v[34:37], v[34:37], v[50:53], 0
	v_add_f32_e64 v66, v88, v66
	v_add_f32_e64 v67, v89, v67
	v_mfma_f32_16x16x32_bf16 v[62:65], v[38:41], v[146:149], v[34:37]
	ds_read_b128 v[38:41], v90 offset:26176
	s_nop 3
	ds_read_b128 v[34:37], v90 offset:26112
	s_waitcnt lgkmcnt(0)
	v_mfma_f32_16x16x32_bf16 v[34:37], v[34:37], v[50:53], 0
	v_add_f32_e64 v62, v124, v62
	v_add_f32_e64 v63, v125, v63
	v_mfma_f32_16x16x32_bf16 v[58:61], v[38:41], v[146:149], v[34:37]
	ds_read_b128 v[38:41], v90 offset:30528
	s_nop 3
	ds_read_b128 v[34:37], v90 offset:30464
	s_waitcnt lgkmcnt(0)
	v_mfma_f32_16x16x32_bf16 v[34:37], v[34:37], v[50:53], 0
	v_add_f32_e64 v58, v128, v58
	v_add_f32_e64 v59, v129, v59
	v_mfma_f32_16x16x32_bf16 v[54:57], v[38:41], v[146:149], v[34:37]
	ds_read_b128 v[38:41], v90 offset:34880
	s_nop 3
	ds_read_b128 v[34:37], v90 offset:34816
	s_waitcnt lgkmcnt(0)
	v_mfma_f32_16x16x32_bf16 v[34:37], v[34:37], v[50:53], 0
	v_add_f32_e64 v54, v132, v54
	v_add_f32_e64 v55, v133, v55
	v_mfma_f32_16x16x32_bf16 v[34:37], v[38:41], v[146:149], v[34:37]
	ds_read_b128 v[38:41], v90 offset:39168
	s_waitcnt lgkmcnt(0)
	v_mfma_f32_16x16x32_bf16 v[38:41], v[38:41], v[50:53], 0
	s_nop 4
	v_add_f32_e64 v34, v136, v34
	v_add_f32_e64 v35, v137, v35
	v_mfma_f32_16x16x32_bf16 v[38:41], v[42:45], v[146:149], v[38:41]
	ds_read_b128 v[42:45], v90 offset:43520
	s_waitcnt lgkmcnt(0)
	v_mfma_f32_16x16x32_bf16 v[42:45], v[42:45], v[50:53], 0
	s_nop 4
	v_add_f32_e64 v40, v40, 0
	v_add_f32_e64 v41, v41, 0
	v_pk_add_f32 v[38:39], v[38:39], 0 op_sel_hi:[1,0]
	v_mfma_f32_16x16x32_bf16 v[42:45], v[46:49], v[146:149], v[42:45]
	ds_read_b128 v[46:49], v90 offset:47872
	s_waitcnt lgkmcnt(0)
	v_mfma_f32_16x16x32_bf16 v[46:49], v[46:49], v[50:53], 0
	s_nop 4
	v_add_f32_e64 v44, v44, 0
	v_add_f32_e64 v45, v45, 0
	v_pk_add_f32 v[42:43], v[42:43], 0 op_sel_hi:[1,0]
	v_mfma_f32_16x16x32_bf16 v[46:49], v[202:205], v[146:149], v[46:49]
	ds_read_b128 v[202:205], v90 offset:52224
	s_waitcnt lgkmcnt(0)
	v_mfma_f32_16x16x32_bf16 v[50:53], v[202:205], v[50:53], 0
	ds_read_b128 v[202:205], v90 offset:52288
	s_nop 3
	v_pk_add_f32 v[48:49], v[48:49], 0 op_sel_hi:[1,0]
	v_pk_add_f32 v[46:47], v[46:47], 0 op_sel_hi:[1,0]
	s_waitcnt lgkmcnt(0)
	v_mfma_f32_16x16x32_bf16 v[50:53], v[202:205], v[146:149], v[50:53]
	v_add_f32_e64 v146, v152, 0
	v_add_f32_e64 v147, v153, 0
	v_pk_add_f32 v[148:149], v[150:151], 0 op_sel_hi:[1,0]
	v_max_f32_e32 v81, v146, v147
	v_max_f32_e32 v77, v148, v149
	v_max3_f32 v75, v75, v77, v81
	v_mov_b32_e32 v77, v76
	v_pk_add_f32 v[150:151], v[76:77], v[156:157]
	v_pk_add_f32 v[152:153], v[78:79], v[154:155]
	v_max_f32_e32 v85, v150, v151
	v_max_f32_e32 v81, v152, v153
	v_max3_f32 v75, v75, v81, v85
	v_mov_b32_e32 v81, v80
	v_pk_add_f32 v[154:155], v[80:81], v[160:161]
	v_pk_add_f32 v[156:157], v[82:83], v[158:159]
	v_max_f32_e32 v123, v154, v155
	v_max_f32_e32 v85, v156, v157
	v_max3_f32 v75, v75, v85, v123
	v_mov_b32_e32 v85, v84
	v_pk_add_f32 v[72:73], v[84:85], v[72:73]
	v_max_f32_e32 v123, v70, v71
	v_max_f32_e32 v127, v72, v73
	v_max3_f32 v123, v75, v123, v127
	v_mov_b32_e32 v75, v74
	v_pk_add_f32 v[68:69], v[74:75], v[68:69]
	v_max_f32_e32 v127, v66, v67
	v_max_f32_e32 v131, v68, v69
	v_max3_f32 v127, v123, v127, v131
	v_mov_b32_e32 v123, v122
	v_pk_add_f32 v[64:65], v[122:123], v[64:65]
	v_max_f32_e32 v131, v62, v63
	v_max_f32_e32 v135, v64, v65
	v_max3_f32 v131, v127, v131, v135
	v_mov_b32_e32 v127, v126
	v_pk_add_f32 v[60:61], v[126:127], v[60:61]
	v_max_f32_e32 v135, v58, v59
	v_max_f32_e32 v158, v60, v61
	v_max3_f32 v135, v131, v135, v158
	v_mov_b32_e32 v131, v130
	v_pk_add_f32 v[56:57], v[130:131], v[56:57]
	v_max_f32_e32 v158, v54, v55
	v_max_f32_e32 v159, v56, v57
	v_max3_f32 v158, v135, v158, v159
	v_mov_b32_e32 v135, v134
	v_pk_add_f32 v[36:37], v[134:135], v[36:37]
	v_max_f32_e32 v159, v34, v35
	v_max_f32_e32 v160, v36, v37
	v_max3_f32 v158, v158, v159, v160
	v_max_f32_e32 v159, v38, v39
	v_max_f32_e32 v160, v40, v41
	v_max3_f32 v158, v158, v159, v160
	v_max_f32_e32 v159, v42, v43
	v_max_f32_e32 v160, v44, v45
	v_max3_f32 v158, v158, v159, v160
	v_max_f32_e32 v159, v46, v47
	v_max_f32_e32 v160, v48, v49
	v_pk_add_f32 v[52:53], v[52:53], 0 op_sel_hi:[1,0]
	v_pk_add_f32 v[50:51], v[50:51], 0 op_sel_hi:[1,0]
	v_max3_f32 v158, v158, v159, v160
	v_max_f32_e32 v159, v50, v51
	v_max_f32_e32 v160, v52, v53
	v_max3_f32 v158, v158, v159, v160
	ds_bpermute_b32 v159, v113, v158
	s_waitcnt lgkmcnt(0)
	v_max_f32_e32 v159, v159, v159
	v_max_f32_e32 v158, v158, v159
	ds_bpermute_b32 v159, v115, v158
	s_waitcnt lgkmcnt(0)
	v_max_f32_e32 v159, v159, v159
	v_max_f32_e32 v210, v158, v159
	v_sub_f32_e32 v149, v149, v210
	v_sub_f32_e32 v146, v146, v210
	v_sub_f32_e32 v148, v148, v210
	v_exp_f32_e32 v158, v149
	v_exp_f32_e32 v149, v146
	v_sub_f32_e32 v146, v147, v210
	v_exp_f32_e32 v148, v148
	v_exp_f32_e32 v159, v146
	v_sub_f32_e32 v70, v70, v210
	v_sub_f32_e32 v67, v67, v210
	v_sub_f32_e32 v66, v66, v210
	v_pk_add_f32 v[146:147], v[148:149], v[158:159]
	v_exp_f32_e32 v66, v66
	v_add_f32_e32 v146, v146, v147
	v_add_f32_e32 v147, 0, v146
	v_sub_f32_e32 v146, v152, v210
	v_exp_f32_e32 v152, v146
	v_sub_f32_e32 v146, v153, v210
	v_exp_f32_e32 v160, v146
	v_sub_f32_e32 v146, v150, v210
	v_exp_f32_e32 v153, v146
	v_sub_f32_e32 v146, v151, v210
	v_exp_f32_e32 v161, v146
	v_sub_f32_e32 v146, v156, v210
	v_exp_f32_e32 v220, v146
	v_sub_f32_e32 v146, v157, v210
	v_pk_add_f32 v[150:151], v[152:153], v[160:161]
	v_exp_f32_e32 v221, v146
	v_sub_f32_e32 v146, v154, v210
	v_exp_f32_e32 v154, v70
	v_sub_f32_e32 v70, v71, v210
	v_pk_add_f32 v[150:151], v[150:151], v[150:151] op_sel_hi:[0,1]
	v_exp_f32_e32 v222, v146
	v_sub_f32_e32 v146, v155, v210
	v_exp_f32_e32 v156, v70
	v_sub_f32_e32 v70, v72, v210
	v_exp_f32_e32 v223, v146
	v_exp_f32_e32 v150, v70
	v_sub_f32_e32 v70, v73, v210
	v_exp_f32_e32 v146, v70
	v_add_f32_e32 v155, v220, v221
	v_add_f32_e32 v157, v222, v223
	v_pk_add_f32 v[70:71], v[154:155], v[156:157]
	v_pk_add_f32 v[72:73], v[150:151], v[146:147]
	v_sub_f32_e32 v62, v62, v210
	v_pk_add_f32 v[70:71], v[70:71], v[72:73]
	v_exp_f32_e32 v72, v67
	v_sub_f32_e32 v67, v68, v210
	v_sub_f32_e32 v68, v69, v210
	v_exp_f32_e32 v67, v67
	v_exp_f32_e32 v73, v68
	v_exp_f32_e32 v147, v62
	v_sub_f32_e32 v62, v63, v210
	v_exp_f32_e32 v151, v62
	v_sub_f32_e32 v62, v64, v210
	v_exp_f32_e32 v155, v62
	v_sub_f32_e32 v62, v65, v210
	v_sub_f32_e32 v58, v58, v210
	v_pk_add_f32 v[68:69], v[66:67], v[72:73]
	v_exp_f32_e32 v157, v62
	v_exp_f32_e32 v62, v58
	v_sub_f32_e32 v58, v59, v210
	v_pk_add_f32 v[68:69], v[68:69], v[68:69] op_sel_hi:[0,1]
	v_exp_f32_e32 v64, v58
	v_sub_f32_e32 v58, v60, v210
	v_pk_add_f32 v[70:71], v[70:71], v[70:71] op_sel_hi:[0,1]
	v_exp_f32_e32 v68, v58
	v_sub_f32_e32 v58, v61, v210
	v_exp_f32_e32 v70, v58
	v_add_f32_e32 v63, v147, v151
	v_add_f32_e32 v65, v155, v157
	v_pk_add_f32 v[58:59], v[62:63], v[64:65]
	v_pk_add_f32 v[60:61], v[68:69], v[70:71]
	v_sub_f32_e32 v55, v55, v210
	v_pk_add_f32 v[58:59], v[58:59], v[60:61]
	v_sub_f32_e32 v54, v54, v210
	v_exp_f32_e32 v60, v55
	v_sub_f32_e32 v55, v56, v210
	v_sub_f32_e32 v56, v57, v210
	v_sub_f32_e32 v34, v34, v210
	v_exp_f32_e32 v54, v54
	v_exp_f32_e32 v55, v55
	v_exp_f32_e32 v61, v56
	v_exp_f32_e32 v63, v34
	v_sub_f32_e32 v34, v35, v210
	v_exp_f32_e32 v65, v34
	v_sub_f32_e32 v34, v36, v210
	v_exp_f32_e32 v69, v34
	v_sub_f32_e32 v34, v37, v210
	v_exp_f32_e32 v71, v34
	v_sub_f32_e32 v34, v38, v210
	v_pk_add_f32 v[56:57], v[54:55], v[60:61]
	v_exp_f32_e32 v202, v34
	v_sub_f32_e32 v34, v39, v210
	v_pk_add_f32 v[56:57], v[56:57], v[56:57] op_sel_hi:[0,1]
	v_exp_f32_e32 v204, v34
	v_sub_f32_e32 v34, v40, v210
	v_pk_add_f32 v[58:59], v[58:59], v[58:59] op_sel_hi:[0,1]
	v_exp_f32_e32 v56, v34
	v_sub_f32_e32 v34, v41, v210
	v_exp_f32_e32 v58, v34
	v_add_f32_e32 v203, v63, v65
	v_add_f32_e32 v205, v69, v71
	v_pk_add_f32 v[34:35], v[202:203], v[204:205]
	v_pk_add_f32 v[36:37], v[56:57], v[58:59]
	s_nop 0
	v_pk_add_f32 v[34:35], v[34:35], v[36:37]
	s_nop 0
	v_pk_add_f32 v[206:207], v[34:35], v[34:35] op_sel_hi:[0,1]
	v_sub_f32_e32 v34, v42, v210
	v_exp_f32_e32 v208, v34
	v_sub_f32_e32 v34, v43, v210
	v_exp_f32_e32 v212, v34
	v_sub_f32_e32 v34, v44, v210
	v_exp_f32_e32 v209, v34
	v_sub_f32_e32 v34, v45, v210
	v_exp_f32_e32 v213, v34
	s_nop 0
	v_pk_add_f32 v[34:35], v[208:209], v[212:213]
	s_nop 0
	v_pk_add_f32 v[214:215], v[34:35], v[34:35] op_sel_hi:[0,1]
	v_sub_f32_e32 v34, v46, v210
	v_exp_f32_e32 v57, v34
	v_sub_f32_e32 v34, v47, v210
	v_exp_f32_e32 v59, v34
	v_sub_f32_e32 v34, v48, v210
	v_exp_f32_e32 v203, v34
	v_sub_f32_e32 v34, v49, v210
	v_exp_f32_e32 v205, v34
	v_sub_f32_e32 v34, v50, v210
	v_exp_f32_e32 v216, v34
	v_sub_f32_e32 v34, v51, v210
	v_exp_f32_e32 v218, v34
	v_sub_f32_e32 v34, v52, v210
	v_exp_f32_e32 v214, v34
	v_sub_f32_e32 v34, v53, v210
	v_exp_f32_e32 v206, v34
	v_add_f32_e32 v217, v57, v59
	v_add_f32_e32 v219, v203, v205
	v_pk_add_f32 v[34:35], v[216:217], v[218:219]
	v_pk_add_f32 v[36:37], v[214:215], v[206:207]
	s_nop 0
	v_pk_add_f32 v[34:35], v[34:35], v[36:37]
	s_nop 0
	v_add_f32_e32 v34, v34, v35
	ds_bpermute_b32 v35, v113, v34
	s_waitcnt lgkmcnt(0)
	v_add_f32_e32 v34, v34, v35
	ds_bpermute_b32 v35, v115, v34
	s_waitcnt lgkmcnt(0)
	v_add_f32_e32 v34, v34, v35
	v_fma_f32 v35, v121, s65, -v210
	v_exp_f32_e32 v35, v35
	s_nop 0
	v_add_f32_e32 v121, v35, v34
	v_cvt_pk_bf16_f32 v34, v148, v158
	v_cvt_pk_bf16_f32 v35, v149, v159
	v_cvt_pk_bf16_f32 v36, v152, v160
	v_cvt_pk_bf16_f32 v37, v153, v161
	v_cvt_pk_bf16_f32 v38, v220, v221
	v_cvt_pk_bf16_f32 v39, v222, v223
	v_cvt_pk_bf16_f32 v40, v154, v156
	v_cvt_pk_bf16_f32 v41, v150, v146
	v_cvt_pk_bf16_f32 v42, v66, v72
	v_cvt_pk_bf16_f32 v43, v67, v73
	v_cvt_pk_bf16_f32 v44, v147, v151
	v_cvt_pk_bf16_f32 v45, v155, v157
	v_cvt_pk_bf16_f32 v46, v62, v64
	v_div_scale_f32 v62, s[26:27], v121, v121, 1.0
	v_cvt_pk_bf16_f32 v47, v68, v70
	v_cvt_pk_bf16_f32 v48, v54, v60
	v_cvt_pk_bf16_f32 v49, v55, v61
	v_cvt_pk_bf16_f32 v50, v63, v65
	v_rcp_f32_e32 v63, v62
	v_add_u32_e32 v70, v189, v164
	v_cvt_pk_bf16_f32 v51, v69, v71
	v_add_u32_e32 v71, 0xd800, v70
	v_fma_f32 v64, -v62, v63, 1.0
	v_fmac_f32_e32 v63, v64, v63
	v_div_scale_f32 v64, vcc, 1.0, v121, 1.0
	v_mul_f32_e32 v65, v64, v63
	v_fma_f32 v66, -v62, v65, v64
	v_fmac_f32_e32 v65, v66, v63
	v_fma_f32 v62, -v62, v65, v64
	v_div_fmas_f32 v62, v62, v63, v65
	v_cvt_pk_bf16_f32 v52, v202, v204
	v_cvt_pk_bf16_f32 v53, v56, v58
	v_cvt_pk_bf16_f32 v54, v208, v212
	v_cvt_pk_bf16_f32 v55, v209, v213
	v_cvt_pk_bf16_f32 v56, v57, v59
	v_cvt_pk_bf16_f32 v57, v203, v205
	v_cvt_pk_bf16_f32 v58, v216, v218
	v_cvt_pk_bf16_f32 v59, v214, v206
	v_cvt_pk_bf16_f32 v60, v91, v91
	v_cvt_pk_bf16_f32 v61, v91, v91
	v_div_fixup_f32 v72, v62, v121, 1.0
	ds_read2_b64 v[62:65], v71 offset0:160 offset1:164
	ds_read2_b64 v[66:69], v71 offset0:168 offset1:172
	s_waitcnt lgkmcnt(1)
	v_mfma_f32_16x16x32_bf16 v[62:65], v[62:65], v[34:37], 0
	v_add_u32_e32 v70, 0xf800, v70
	ds_read_b128 v[154:157], v90 offset:21952
	ds_read_b128 v[158:161], v90 offset:26304
	s_waitcnt lgkmcnt(2)
	v_mfma_f32_16x16x32_bf16 v[62:65], v[66:69], v[38:41], v[62:65]
	ds_read2_b64 v[66:69], v71 offset0:176 offset1:180
	ds_read_b128 v[202:205], v90 offset:30656
	ds_read_b128 v[206:209], v90 offset:35008
	s_waitcnt lgkmcnt(2)
	v_mfma_f32_16x16x32_bf16 v[62:65], v[66:69], v[42:45], v[62:65]
	ds_read2_b64 v[66:69], v71 offset0:184 offset1:188
	ds_read_b128 v[212:215], v90 offset:39360
	ds_read_b128 v[216:219], v90 offset:43712
	s_waitcnt lgkmcnt(2)
	v_mfma_f32_16x16x32_bf16 v[62:65], v[66:69], v[46:49], v[62:65]
	ds_read2_b64 v[66:69], v71 offset0:192 offset1:196
	ds_read_b128 v[220:223], v90 offset:48064
	s_waitcnt lgkmcnt(1)
	v_mfma_f32_16x16x32_bf16 v[62:65], v[66:69], v[50:53], v[62:65]
	ds_read2_b64 v[66:69], v71 offset0:200 offset1:204
	s_waitcnt lgkmcnt(0)
	v_mfma_f32_16x16x32_bf16 v[62:65], v[66:69], v[54:57], v[62:65]
	ds_read2_b64 v[66:69], v71 offset0:208 offset1:212
	s_waitcnt lgkmcnt(0)
	v_mfma_f32_16x16x32_bf16 v[62:65], v[66:69], v[58:61], v[62:65]
	ds_read2_b64 v[66:69], v70 offset0:88 offset1:92
	s_nop 6
	v_pk_mul_f32 v[146:147], v[72:73], v[64:65] op_sel_hi:[0,1]
	v_pk_mul_f32 v[148:149], v[72:73], v[62:63] op_sel_hi:[0,1]
	ds_read2_b64 v[62:65], v70 offset0:80 offset1:84
	s_waitcnt lgkmcnt(0)
	v_mfma_f32_16x16x32_bf16 v[62:65], v[62:65], v[34:37], 0
	v_mfma_f32_16x16x32_bf16 v[62:65], v[66:69], v[38:41], v[62:65]
	ds_read2_b64 v[66:69], v70 offset0:96 offset1:100
	s_waitcnt lgkmcnt(0)
	v_mfma_f32_16x16x32_bf16 v[62:65], v[66:69], v[42:45], v[62:65]
	ds_read2_b64 v[66:69], v70 offset0:104 offset1:108
	s_waitcnt lgkmcnt(0)
	v_mfma_f32_16x16x32_bf16 v[62:65], v[66:69], v[46:49], v[62:65]
	ds_read2_b64 v[66:69], v70 offset0:112 offset1:116
	s_waitcnt lgkmcnt(0)
	v_mfma_f32_16x16x32_bf16 v[62:65], v[66:69], v[50:53], v[62:65]
	ds_read2_b64 v[66:69], v70 offset0:120 offset1:124
	s_waitcnt lgkmcnt(0)
	v_mfma_f32_16x16x32_bf16 v[62:65], v[66:69], v[54:57], v[62:65]
	ds_read2_b64 v[66:69], v70 offset0:128 offset1:132
	v_add_u32_e32 v70, 0x3800, v190
	ds_read2_b64 v[150:153], v70 offset0:104 offset1:108
	s_waitcnt lgkmcnt(1)
	v_mfma_f32_16x16x32_bf16 v[64:67], v[66:69], v[58:61], v[62:65]
	s_nop 7
	v_pk_mul_f32 v[62:63], v[72:73], v[66:67] op_sel_hi:[0,1]
	ds_read2_b64 v[66:69], v70 offset0:96 offset1:100
	s_waitcnt lgkmcnt(0)
	v_mfma_f32_16x16x32_bf16 v[66:69], v[66:69], v[34:37], 0
	v_mul_f32_e64 v64, v72, v64
	v_mul_f32_e64 v65, v72, v65
	v_mfma_f32_16x16x32_bf16 v[66:69], v[150:153], v[38:41], v[66:69]
	ds_read2_b64 v[150:153], v70 offset0:112 offset1:116
	s_waitcnt lgkmcnt(0)
	v_mfma_f32_16x16x32_bf16 v[66:69], v[150:153], v[42:45], v[66:69]
	ds_read2_b64 v[150:153], v70 offset0:120 offset1:124
	s_waitcnt lgkmcnt(0)
	v_mfma_f32_16x16x32_bf16 v[66:69], v[150:153], v[46:49], v[66:69]
	ds_read2_b64 v[150:153], v70 offset0:128 offset1:132
	s_waitcnt lgkmcnt(0)
	v_mfma_f32_16x16x32_bf16 v[66:69], v[150:153], v[50:53], v[66:69]
	ds_read2_b64 v[150:153], v70 offset0:136 offset1:140
	s_waitcnt lgkmcnt(0)
	v_mfma_f32_16x16x32_bf16 v[66:69], v[150:153], v[54:57], v[66:69]
	ds_read2_b64 v[150:153], v70 offset0:144 offset1:148
	v_add_u32_e32 v70, 0x5800, v190
	s_waitcnt lgkmcnt(0)
	v_mfma_f32_16x16x32_bf16 v[66:69], v[150:153], v[58:61], v[66:69]
	ds_read2_b64 v[150:153], v70 offset0:16 offset1:20
	s_nop 6
	v_pk_mul_f32 v[66:67], v[72:73], v[66:67] op_sel_hi:[0,1]
	s_waitcnt lgkmcnt(0)
	v_mfma_f32_16x16x32_bf16 v[34:37], v[150:153], v[34:37], 0
	ds_read2_b64 v[150:153], v70 offset0:24 offset1:28
	v_pk_mul_f32 v[68:69], v[72:73], v[68:69] op_sel_hi:[0,1]
	s_waitcnt lgkmcnt(0)
	v_mfma_f32_16x16x32_bf16 v[34:37], v[150:153], v[38:41], v[34:37]
	ds_read2_b64 v[38:41], v70 offset0:32 offset1:36
	ds_read_b128 v[150:153], v90 offset:17600
	s_waitcnt lgkmcnt(1)
	v_mfma_f32_16x16x32_bf16 v[34:37], v[38:41], v[42:45], v[34:37]
	ds_read2_b64 v[38:41], v70 offset0:40 offset1:44
	ds_read_b128 v[42:45], v90 offset:128
	s_waitcnt lgkmcnt(1)
	v_mfma_f32_16x16x32_bf16 v[34:37], v[38:41], v[46:49], v[34:37]
	ds_read2_b64 v[38:41], v70 offset0:48 offset1:52
	ds_read_b128 v[46:49], v90 offset:192
	s_waitcnt lgkmcnt(1)
	v_mfma_f32_16x16x32_bf16 v[34:37], v[38:41], v[50:53], v[34:37]
	ds_read2_b64 v[38:41], v70 offset0:56 offset1:60
	ds_read_b128 v[50:53], v90 offset:4544
	s_waitcnt lgkmcnt(1)
	v_mfma_f32_16x16x32_bf16 v[34:37], v[38:41], v[54:57], v[34:37]
	ds_read2_b64 v[38:41], v70 offset0:64 offset1:68
	ds_read_b128 v[54:57], v90 offset:8896
	s_waitcnt lgkmcnt(1)
	v_mfma_f32_16x16x32_bf16 v[34:37], v[38:41], v[58:61], v[34:37]
	v_cndmask_b32_e64 v41, v33, v17, s[0:1]
	v_cndmask_b32_e64 v40, v32, v16, s[0:1]
	v_cndmask_b32_e64 v39, v31, v15, s[0:1]
	s_nop 4
	v_pk_mul_f32 v[70:71], v[72:73], v[36:37] op_sel_hi:[0,1]
	v_pk_mul_f32 v[72:73], v[72:73], v[34:35] op_sel_hi:[0,1]
	v_cndmask_b32_e64 v37, v29, v13, s[0:1]
	v_cndmask_b32_e64 v36, v28, v12, s[0:1]
	v_cndmask_b32_e64 v35, v27, v11, s[0:1]
	v_cndmask_b32_e64 v34, v26, v10, s[0:1]
	v_cndmask_b32_e64 v38, v30, v14, s[0:1]
	ds_read_b128 v[58:61], v90 offset:13248
	v_mfma_f32_16x16x32_bf16 v[42:45], v[42:45], v[34:37], 0
	v_mfma_f32_16x16x32_bf16 v[42:45], v[46:49], v[38:41], v[42:45]
	ds_read_b128 v[46:49], v90 offset:4480
	s_waitcnt lgkmcnt(0)
	v_mfma_f32_16x16x32_bf16 v[46:49], v[46:49], v[34:37], 0
	v_mfma_f32_16x16x32_bf16 v[46:49], v[50:53], v[38:41], v[46:49]
	ds_read_b128 v[50:53], v90 offset:8832
	s_waitcnt lgkmcnt(0)
	v_mfma_f32_16x16x32_bf16 v[50:53], v[50:53], v[34:37], 0
	v_mfma_f32_16x16x32_bf16 v[50:53], v[54:57], v[38:41], v[50:53]
	ds_read_b128 v[54:57], v90 offset:13184
	s_waitcnt lgkmcnt(0)
	v_mfma_f32_16x16x32_bf16 v[54:57], v[54:57], v[34:37], 0
	v_mfma_f32_16x16x32_bf16 v[54:57], v[58:61], v[38:41], v[54:57]
	ds_read_b128 v[58:61], v90 offset:17536
	s_waitcnt lgkmcnt(0)
	v_mfma_f32_16x16x32_bf16 v[58:61], v[58:61], v[34:37], 0
	v_mfma_f32_16x16x32_bf16 v[58:61], v[150:153], v[38:41], v[58:61]
	ds_read_b128 v[150:153], v90 offset:21888
	s_waitcnt lgkmcnt(0)
	v_mfma_f32_16x16x32_bf16 v[150:153], v[150:153], v[34:37], 0
	v_mfma_f32_16x16x32_bf16 v[150:153], v[154:157], v[38:41], v[150:153]
	ds_read_b128 v[154:157], v90 offset:26240
	s_waitcnt lgkmcnt(0)
	v_mfma_f32_16x16x32_bf16 v[154:157], v[154:157], v[34:37], 0
	v_mfma_f32_16x16x32_bf16 v[154:157], v[158:161], v[38:41], v[154:157]
	ds_read_b128 v[158:161], v90 offset:30592
	s_waitcnt lgkmcnt(0)
	v_mfma_f32_16x16x32_bf16 v[158:161], v[158:161], v[34:37], 0
	v_mfma_f32_16x16x32_bf16 v[158:161], v[202:205], v[38:41], v[158:161]
	ds_read_b128 v[202:205], v90 offset:34944
	s_waitcnt lgkmcnt(0)
	v_mfma_f32_16x16x32_bf16 v[202:205], v[202:205], v[34:37], 0
	v_mfma_f32_16x16x32_bf16 v[202:205], v[206:209], v[38:41], v[202:205]
	ds_read_b128 v[206:209], v90 offset:39296
	s_waitcnt lgkmcnt(0)
	v_mfma_f32_16x16x32_bf16 v[206:209], v[206:209], v[34:37], 0
	v_mfma_f32_16x16x32_bf16 v[206:209], v[212:215], v[38:41], v[206:209]
	ds_read_b128 v[212:215], v90 offset:43648
	s_waitcnt lgkmcnt(0)
	v_mfma_f32_16x16x32_bf16 v[212:215], v[212:215], v[34:37], 0
	v_mfma_f32_16x16x32_bf16 v[212:215], v[216:219], v[38:41], v[212:215]
	ds_read_b128 v[216:219], v90 offset:48000
	s_waitcnt lgkmcnt(0)
	v_mfma_f32_16x16x32_bf16 v[216:219], v[216:219], v[34:37], 0
	v_mfma_f32_16x16x32_bf16 v[216:219], v[220:223], v[38:41], v[216:219]
	ds_read_b128 v[220:223], v90 offset:52352
	s_waitcnt lgkmcnt(0)
	v_mfma_f32_16x16x32_bf16 v[34:37], v[220:223], v[34:37], 0
	ds_read_b128 v[220:223], v90 offset:52416
	global_load_dword v90, v[96:97], off offset:16
	s_waitcnt vmcnt(0)
	v_mul_f32_e32 v121, 0x3fb8aa3b, v90
	s_waitcnt lgkmcnt(0)
	v_mfma_f32_16x16x32_bf16 v[34:37], v[220:223], v[38:41], v[34:37]
	v_add_f32_e64 v38, v44, 0
	v_add_f32_e64 v39, v45, 0
	v_pk_add_f32 v[40:41], v[42:43], 0 op_sel_hi:[1,0]
	v_max_f32_e32 v43, v38, v39
	v_max_f32_e32 v42, v40, v41
	v_max3_f32 v121, v121, v42, v43
	v_pk_add_f32 v[42:43], v[76:77], v[48:49]
	v_pk_add_f32 v[44:45], v[78:79], v[46:47]
	v_max_f32_e32 v47, v42, v43
	v_max_f32_e32 v46, v44, v45
	v_max3_f32 v77, v121, v46, v47
	v_pk_add_f32 v[46:47], v[80:81], v[52:53]
	v_pk_add_f32 v[48:49], v[82:83], v[50:51]
	v_max_f32_e32 v51, v46, v47
	v_max_f32_e32 v50, v48, v49
	v_max3_f32 v77, v77, v50, v51
	v_pk_add_f32 v[50:51], v[84:85], v[56:57]
	v_pk_add_f32 v[52:53], v[86:87], v[54:55]
	v_max_f32_e32 v55, v50, v51
	v_max_f32_e32 v54, v52, v53
	v_max3_f32 v77, v77, v54, v55
	v_pk_add_f32 v[54:55], v[74:75], v[60:61]
	v_pk_add_f32 v[56:57], v[88:89], v[58:59]
	v_max_f32_e32 v59, v54, v55
	v_max_f32_e32 v58, v56, v57
	v_max3_f32 v75, v77, v58, v59
	v_pk_add_f32 v[58:59], v[122:123], v[152:153]
	v_pk_add_f32 v[60:61], v[124:125], v[150:151]
	v_max_f32_e32 v81, v58, v59
	v_max_f32_e32 v77, v60, v61
	v_pk_add_f32 v[150:151], v[126:127], v[156:157]
	v_pk_add_f32 v[152:153], v[128:129], v[154:155]
	v_max3_f32 v75, v75, v77, v81
	v_max_f32_e32 v77, v152, v153
	v_max_f32_e32 v81, v150, v151
	v_pk_add_f32 v[154:155], v[130:131], v[160:161]
	v_pk_add_f32 v[156:157], v[132:133], v[158:159]
	v_max3_f32 v75, v75, v77, v81
	v_max_f32_e32 v77, v156, v157
	v_max_f32_e32 v81, v154, v155
	v_pk_add_f32 v[158:159], v[134:135], v[204:205]
	v_pk_add_f32 v[160:161], v[136:137], v[202:203]
	v_max3_f32 v75, v75, v77, v81
	v_max_f32_e32 v77, v160, v161
	v_max_f32_e32 v81, v158, v159
	v_pk_add_f32 v[202:203], v[208:209], 0 op_sel_hi:[1,0]
	v_pk_add_f32 v[204:205], v[206:207], 0 op_sel_hi:[1,0]
	v_max3_f32 v75, v75, v77, v81
	v_max_f32_e32 v77, v204, v205
	v_max_f32_e32 v81, v202, v203
	v_pk_add_f32 v[206:207], v[214:215], 0 op_sel_hi:[1,0]
	v_pk_add_f32 v[208:209], v[212:213], 0 op_sel_hi:[1,0]
	v_max3_f32 v75, v75, v77, v81
	v_max_f32_e32 v77, v208, v209
	v_max_f32_e32 v81, v206, v207
	v_pk_add_f32 v[212:213], v[218:219], 0 op_sel_hi:[1,0]
	v_pk_add_f32 v[214:215], v[216:217], 0 op_sel_hi:[1,0]
	v_max3_f32 v75, v75, v77, v81
	v_max_f32_e32 v77, v214, v215
	v_max_f32_e32 v81, v212, v213
	v_pk_add_f32 v[36:37], v[36:37], 0 op_sel_hi:[1,0]
	v_pk_add_f32 v[34:35], v[34:35], 0 op_sel_hi:[1,0]
	v_max3_f32 v75, v75, v77, v81
	v_max_f32_e32 v77, v34, v35
	v_max_f32_e32 v81, v36, v37
	v_max3_f32 v75, v75, v77, v81
	ds_bpermute_b32 v77, v113, v75
	s_waitcnt lgkmcnt(0)
	v_max_f32_e32 v77, v77, v77
	v_max_f32_e32 v75, v75, v77
	ds_bpermute_b32 v77, v115, v75
	s_waitcnt lgkmcnt(0)
	v_max_f32_e32 v77, v77, v77
	v_max_f32_e32 v75, v75, v77
	v_sub_f32_e32 v41, v41, v75
	v_sub_f32_e32 v38, v38, v75
	v_sub_f32_e32 v40, v40, v75
	v_exp_f32_e32 v216, v41
	v_exp_f32_e32 v41, v38
	v_sub_f32_e32 v38, v39, v75
	v_exp_f32_e32 v40, v40
	v_exp_f32_e32 v217, v38
	v_sub_f32_e32 v34, v34, v75
	v_pk_add_f32 v[38:39], v[40:41], v[216:217]
	s_nop 0
	v_add_f32_e32 v38, v38, v39
	v_add_f32_e32 v219, 0, v38
	v_sub_f32_e32 v38, v44, v75
	v_exp_f32_e32 v44, v38
	v_sub_f32_e32 v38, v45, v75
	v_exp_f32_e32 v220, v38
	v_sub_f32_e32 v38, v42, v75
	v_exp_f32_e32 v45, v38
	v_sub_f32_e32 v38, v43, v75
	v_exp_f32_e32 v221, v38
	s_nop 0
	v_pk_add_f32 v[38:39], v[44:45], v[220:221]
	s_nop 0
	v_pk_add_f32 v[222:223], v[38:39], v[38:39] op_sel_hi:[0,1]
	v_sub_f32_e32 v38, v48, v75
	v_exp_f32_e32 v77, v38
	v_sub_f32_e32 v38, v49, v75
	v_exp_f32_e32 v81, v38
	v_sub_f32_e32 v38, v46, v75
	v_exp_f32_e32 v85, v38
	v_sub_f32_e32 v38, v47, v75
	v_exp_f32_e32 v121, v38
	v_sub_f32_e32 v38, v52, v75
	v_exp_f32_e32 v46, v38
	v_sub_f32_e32 v38, v53, v75
	v_exp_f32_e32 v48, v38
	v_sub_f32_e32 v38, v50, v75
	v_exp_f32_e32 v222, v38
	v_sub_f32_e32 v38, v51, v75
	v_exp_f32_e32 v218, v38
	v_add_f32_e32 v47, v77, v81
	v_add_f32_e32 v49, v85, v121
	v_pk_add_f32 v[38:39], v[46:47], v[48:49]
	v_pk_add_f32 v[42:43], v[222:223], v[218:219]
	s_nop 0
	v_pk_add_f32 v[38:39], v[38:39], v[42:43]
	s_nop 0
	v_pk_add_f32 v[52:53], v[38:39], v[38:39] op_sel_hi:[0,1]
	v_sub_f32_e32 v38, v56, v75
	v_exp_f32_e32 v50, v38
	v_sub_f32_e32 v38, v57, v75
	v_exp_f32_e32 v56, v38
	v_sub_f32_e32 v38, v54, v75
	v_exp_f32_e32 v51, v38
	v_sub_f32_e32 v38, v55, v75
	v_exp_f32_e32 v57, v38
	s_nop 0
	v_pk_add_f32 v[38:39], v[50:51], v[56:57]
	s_nop 0
	v_pk_add_f32 v[54:55], v[38:39], v[38:39] op_sel_hi:[0,1]
	v_sub_f32_e32 v38, v60, v75
	v_exp_f32_e32 v49, v38
	v_sub_f32_e32 v38, v61, v75
	v_exp_f32_e32 v123, v38
	v_sub_f32_e32 v38, v58, v75
	v_exp_f32_e32 v127, v38
	v_sub_f32_e32 v38, v59, v75
	v_exp_f32_e32 v131, v38
	v_sub_f32_e32 v38, v152, v75
	v_exp_f32_e32 v58, v38
	v_sub_f32_e32 v38, v153, v75
	v_exp_f32_e32 v60, v38
	v_sub_f32_e32 v38, v150, v75
	v_exp_f32_e32 v54, v38
	v_sub_f32_e32 v38, v151, v75
	v_exp_f32_e32 v52, v38
	v_add_f32_e32 v59, v49, v123
	v_add_f32_e32 v61, v127, v131
	v_pk_add_f32 v[38:39], v[58:59], v[60:61]
	v_pk_add_f32 v[42:43], v[54:55], v[52:53]
	s_nop 0
	v_pk_add_f32 v[38:39], v[38:39], v[42:43]
	s_nop 0
	v_pk_add_f32 v[150:151], v[38:39], v[38:39] op_sel_hi:[0,1]
	v_sub_f32_e32 v38, v156, v75
	v_exp_f32_e32 v152, v38
	v_sub_f32_e32 v38, v157, v75
	v_exp_f32_e32 v156, v38
	v_sub_f32_e32 v38, v154, v75
	v_exp_f32_e32 v153, v38
	v_sub_f32_e32 v38, v155, v75
	v_exp_f32_e32 v157, v38
	s_nop 0
	v_pk_add_f32 v[38:39], v[152:153], v[156:157]
	s_nop 0
	v_pk_add_f32 v[154:155], v[38:39], v[38:39] op_sel_hi:[0,1]
	v_sub_f32_e32 v38, v160, v75
	v_exp_f32_e32 v55, v38
	v_sub_f32_e32 v38, v161, v75
	v_exp_f32_e32 v59, v38
	v_sub_f32_e32 v38, v158, v75
	v_exp_f32_e32 v61, v38
	v_sub_f32_e32 v38, v159, v75
	v_exp_f32_e32 v135, v38
	v_sub_f32_e32 v38, v204, v75
	v_exp_f32_e32 v158, v38
	v_sub_f32_e32 v38, v205, v75
	v_exp_f32_e32 v160, v38
	v_sub_f32_e32 v38, v202, v75
	v_exp_f32_e32 v154, v38
	v_sub_f32_e32 v38, v203, v75
	v_exp_f32_e32 v150, v38
	v_add_f32_e32 v159, v55, v59
	v_add_f32_e32 v161, v61, v135
	v_pk_add_f32 v[38:39], v[158:159], v[160:161]
	v_pk_add_f32 v[42:43], v[154:155], v[150:151]
	s_nop 0
	v_pk_add_f32 v[38:39], v[38:39], v[42:43]
	s_nop 0
	v_pk_add_f32 v[202:203], v[38:39], v[38:39] op_sel_hi:[0,1]
	v_sub_f32_e32 v38, v208, v75
	v_exp_f32_e32 v204, v38
	v_sub_f32_e32 v38, v209, v75
	v_exp_f32_e32 v208, v38
	v_sub_f32_e32 v38, v206, v75
	v_exp_f32_e32 v205, v38
	v_sub_f32_e32 v38, v207, v75
	v_exp_f32_e32 v209, v38
	s_nop 0
	v_pk_add_f32 v[38:39], v[204:205], v[208:209]
	s_nop 0
	v_pk_add_f32 v[206:207], v[38:39], v[38:39] op_sel_hi:[0,1]
	v_sub_f32_e32 v38, v214, v75
	v_exp_f32_e32 v151, v38
	v_sub_f32_e32 v38, v215, v75
	v_exp_f32_e32 v155, v38
	v_sub_f32_e32 v38, v212, v75
	v_exp_f32_e32 v212, v34
	v_sub_f32_e32 v34, v35, v75
	v_exp_f32_e32 v159, v38
	v_sub_f32_e32 v38, v213, v75
	v_exp_f32_e32 v214, v34
	v_sub_f32_e32 v34, v36, v75
	v_exp_f32_e32 v161, v38
	v_exp_f32_e32 v206, v34
	v_sub_f32_e32 v34, v37, v75
	v_exp_f32_e32 v202, v34
	v_add_f32_e32 v213, v151, v155
	v_add_f32_e32 v215, v159, v161
	v_pk_add_f32 v[34:35], v[212:213], v[214:215]
	v_pk_add_f32 v[36:37], v[206:207], v[202:203]
	v_cvt_pk_bf16_f32 v38, v40, v216
	v_cvt_pk_bf16_f32 v39, v41, v217
	v_cvt_pk_bf16_f32 v40, v44, v220
	v_cvt_pk_bf16_f32 v41, v45, v221
	v_cvt_pk_bf16_f32 v42, v77, v81
	s_nop 0
	v_pk_add_f32 v[34:35], v[34:35], v[36:37]
	v_cvt_pk_bf16_f32 v43, v85, v121
	v_cvt_pk_bf16_f32 v44, v46, v48
	v_cvt_pk_bf16_f32 v45, v222, v218
	v_cvt_pk_bf16_f32 v46, v50, v56
	v_cvt_pk_bf16_f32 v47, v51, v57
	s_nop 0
	v_add_f32_e32 v34, v34, v35
	ds_bpermute_b32 v35, v113, v34
	v_cvt_pk_bf16_f32 v48, v49, v123
	v_cvt_pk_bf16_f32 v49, v127, v131
	v_cvt_pk_bf16_f32 v50, v58, v60
	v_cvt_pk_bf16_f32 v51, v54, v52
	s_waitcnt lgkmcnt(0)
	v_add_f32_e32 v34, v34, v35
	ds_bpermute_b32 v35, v115, v34
	v_cvt_pk_bf16_f32 v52, v152, v156
	v_cvt_pk_bf16_f32 v53, v153, v157
	v_cvt_pk_bf16_f32 v54, v55, v59
	v_cvt_pk_bf16_f32 v55, v61, v135
	s_waitcnt lgkmcnt(0)
	v_add_f32_e32 v34, v34, v35
	v_fma_f32 v35, v90, s65, -v75
	v_exp_f32_e32 v35, v35
	v_cvt_pk_bf16_f32 v56, v158, v160
	v_cvt_pk_bf16_f32 v57, v154, v150
	v_cvt_pk_bf16_f32 v58, v204, v208
	v_cvt_pk_bf16_f32 v59, v205, v209
	v_cvt_pk_bf16_f32 v60, v151, v155
	s_nop 0
	v_add_f32_e32 v75, v35, v34
	v_div_scale_f32 v77, s[0:1], v75, v75, 1.0
	v_rcp_f32_e32 v81, v77
	v_cvt_pk_bf16_f32 v61, v159, v161
	v_cvt_pk_bf16_f32 v34, v212, v214
	v_cvt_pk_bf16_f32 v35, v206, v202
	v_cvt_pk_bf16_f32 v36, v91, v91
	v_cvt_pk_bf16_f32 v37, v91, v91
	s_nop 0
	v_fma_f32 v85, -v77, v81, 1.0
	v_fmac_f32_e32 v81, v85, v81
	v_div_scale_f32 v85, vcc, 1.0, v75, 1.0
	v_mul_f32_e32 v90, v85, v81
	v_fma_f32 v121, -v77, v90, v85
	v_fmac_f32_e32 v90, v121, v81
	v_fma_f32 v77, -v77, v90, v85
	v_div_fmas_f32 v77, v77, v81, v90
	v_div_fixup_f32 v90, v77, v75, 1.0
	v_add_u32_e32 v75, v191, v164
	v_add_u32_e32 v75, 0xd800, v75
	ds_read2_b64 v[150:153], v75 offset0:160 offset1:164
	ds_read2_b64 v[154:157], v75 offset0:168 offset1:172
	s_waitcnt lgkmcnt(1)
	v_mfma_f32_16x16x32_bf16 v[150:153], v[150:153], v[38:41], 0
	s_waitcnt lgkmcnt(0)
	v_mfma_f32_16x16x32_bf16 v[150:153], v[154:157], v[42:45], v[150:153]
	ds_read2_b64 v[154:157], v75 offset0:176 offset1:180
	s_waitcnt lgkmcnt(0)
	v_mfma_f32_16x16x32_bf16 v[150:153], v[154:157], v[46:49], v[150:153]
	ds_read2_b64 v[154:157], v75 offset0:184 offset1:188
	s_waitcnt lgkmcnt(0)
	v_mfma_f32_16x16x32_bf16 v[150:153], v[154:157], v[50:53], v[150:153]
	ds_read2_b64 v[154:157], v75 offset0:192 offset1:196
	s_waitcnt lgkmcnt(0)
	v_mfma_f32_16x16x32_bf16 v[150:153], v[154:157], v[54:57], v[150:153]
	ds_read2_b64 v[154:157], v75 offset0:200 offset1:204
	s_waitcnt lgkmcnt(0)
	v_mfma_f32_16x16x32_bf16 v[150:153], v[154:157], v[58:61], v[150:153]
	ds_read2_b64 v[154:157], v75 offset0:208 offset1:212
	v_add_u32_e32 v75, 0x9000, v190
	ds_read2_b64 v[158:161], v75 offset0:120 offset1:124
	s_waitcnt lgkmcnt(1)
	v_mfma_f32_16x16x32_bf16 v[152:155], v[154:157], v[34:37], v[150:153]
	s_nop 7
	v_pk_mul_f32 v[150:151], v[90:91], v[154:155] op_sel_hi:[0,1]
	ds_read2_b64 v[154:157], v75 offset0:112 offset1:116
	s_waitcnt lgkmcnt(0)
	v_mfma_f32_16x16x32_bf16 v[154:157], v[154:157], v[38:41], 0
	v_mul_f32_e64 v152, v90, v152
	v_mul_f32_e64 v153, v90, v153
	v_mfma_f32_16x16x32_bf16 v[154:157], v[158:161], v[42:45], v[154:157]
	ds_read2_b64 v[158:161], v75 offset0:128 offset1:132
	s_waitcnt lgkmcnt(0)
	v_mfma_f32_16x16x32_bf16 v[154:157], v[158:161], v[46:49], v[154:157]
	ds_read2_b64 v[158:161], v75 offset0:136 offset1:140
	s_waitcnt lgkmcnt(0)
	v_mfma_f32_16x16x32_bf16 v[154:157], v[158:161], v[50:53], v[154:157]
	ds_read2_b64 v[158:161], v75 offset0:144 offset1:148
	s_waitcnt lgkmcnt(0)
	v_mfma_f32_16x16x32_bf16 v[154:157], v[158:161], v[54:57], v[154:157]
	ds_read2_b64 v[158:161], v75 offset0:152 offset1:156
	s_waitcnt lgkmcnt(0)
	v_mfma_f32_16x16x32_bf16 v[154:157], v[158:161], v[58:61], v[154:157]
	ds_read2_b64 v[158:161], v75 offset0:160 offset1:164
	v_add_u32_e32 v75, 0xb000, v190
	ds_read2_b64 v[202:205], v75 offset0:40 offset1:44
	s_waitcnt lgkmcnt(1)
	v_mfma_f32_16x16x32_bf16 v[154:157], v[158:161], v[34:37], v[154:157]
	ds_read2_b64 v[158:161], v75 offset0:32 offset1:36
	s_nop 6
	v_pk_mul_f32 v[154:155], v[90:91], v[154:155] op_sel_hi:[0,1]
	s_waitcnt lgkmcnt(0)
	v_mfma_f32_16x16x32_bf16 v[158:161], v[158:161], v[38:41], 0
	v_mul_f32_e64 v156, v90, v156
	v_mul_f32_e64 v157, v90, v157
	v_mfma_f32_16x16x32_bf16 v[158:161], v[202:205], v[42:45], v[158:161]
	ds_read2_b64 v[202:205], v75 offset0:48 offset1:52
	s_waitcnt lgkmcnt(0)
	v_mfma_f32_16x16x32_bf16 v[158:161], v[202:205], v[46:49], v[158:161]
	ds_read2_b64 v[202:205], v75 offset0:56 offset1:60
	s_waitcnt lgkmcnt(0)
	v_mfma_f32_16x16x32_bf16 v[158:161], v[202:205], v[50:53], v[158:161]
	ds_read2_b64 v[202:205], v75 offset0:64 offset1:68
	s_waitcnt lgkmcnt(0)
	v_mfma_f32_16x16x32_bf16 v[158:161], v[202:205], v[54:57], v[158:161]
	ds_read2_b64 v[202:205], v75 offset0:72 offset1:76
	s_waitcnt lgkmcnt(0)
	v_mfma_f32_16x16x32_bf16 v[158:161], v[202:205], v[58:61], v[158:161]
	ds_read2_b64 v[202:205], v75 offset0:80 offset1:84
	v_add_u32_e32 v75, 0xc800, v190
	s_waitcnt lgkmcnt(0)
	v_mfma_f32_16x16x32_bf16 v[202:205], v[202:205], v[34:37], v[158:161]
	s_nop 7
	v_pk_mul_f32 v[158:159], v[90:91], v[204:205] op_sel_hi:[0,1]
	v_pk_mul_f32 v[160:161], v[90:91], v[202:203] op_sel_hi:[0,1]
	ds_read2_b64 v[202:205], v75 offset0:208 offset1:212
	s_waitcnt lgkmcnt(0)
	v_mfma_f32_16x16x32_bf16 v[38:41], v[202:205], v[38:41], 0
	ds_read2_b64 v[202:205], v75 offset0:216 offset1:220
	s_waitcnt lgkmcnt(0)
	v_mfma_f32_16x16x32_bf16 v[38:41], v[202:205], v[42:45], v[38:41]
	ds_read2_b64 v[42:45], v75 offset0:224 offset1:228
	s_waitcnt lgkmcnt(0)
	v_mfma_f32_16x16x32_bf16 v[38:41], v[42:45], v[46:49], v[38:41]
	ds_read2_b64 v[42:45], v75 offset0:232 offset1:236
	s_waitcnt lgkmcnt(0)
	v_mfma_f32_16x16x32_bf16 v[38:41], v[42:45], v[50:53], v[38:41]
	ds_read2_b64 v[42:45], v75 offset0:240 offset1:244
	s_waitcnt lgkmcnt(0)
	v_mfma_f32_16x16x32_bf16 v[38:41], v[42:45], v[54:57], v[38:41]
	ds_read2_b64 v[42:45], v75 offset0:248 offset1:252
	s_waitcnt lgkmcnt(0)
	v_mfma_f32_16x16x32_bf16 v[38:41], v[42:45], v[58:61], v[38:41]
	v_add_u32_e32 v42, 0xd000, v190
	ds_read2_b64 v[42:45], v42 offset1:4
	s_waitcnt lgkmcnt(0)
	v_mfma_f32_16x16x32_bf16 v[34:37], v[42:45], v[34:37], v[38:41]
	v_mov_b32_e32 v42, v147
	v_mov_b32_e32 v43, v63
	v_pk_mul_f32 v[42:43], v[42:43], v[42:43]
	s_nop 4
	v_pk_mul_f32 v[38:39], v[90:91], v[36:37] op_sel_hi:[0,1]
	v_mov_b32_e32 v36, v149
	v_mov_b32_e32 v37, v65
	v_pk_mul_f32 v[40:41], v[90:91], v[34:35] op_sel_hi:[0,1]
	v_mov_b32_e32 v34, v148
	v_mov_b32_e32 v35, v64
	v_pk_mul_f32 v[36:37], v[36:37], v[36:37]
	s_nop 0
	v_pk_fma_f32 v[34:35], v[34:35], v[34:35], v[36:37]
	v_mov_b32_e32 v36, v146
	v_mov_b32_e32 v37, v62
	v_pk_fma_f32 v[36:37], v[36:37], v[36:37], v[42:43]
	v_pk_mul_f32 v[42:43], v[66:67], v[66:67]
	v_pk_add_f32 v[34:35], v[34:35], v[36:37]
	v_pk_mul_f32 v[36:37], v[68:69], v[68:69]
	v_pk_add_f32 v[34:35], v[34:35], v[34:35] op_sel:[0,1] op_sel_hi:[1,0]
	v_pk_mov_b32 v[44:45], v[42:43], v[36:37] op_sel:[1,0]
	v_mov_b32_e32 v43, v37
	v_pk_add_f32 v[36:37], v[44:45], v[42:43]
	v_mul_f32_e32 v42, v152, v152
	v_mul_f32_e32 v43, v153, v153
	v_pk_add_f32 v[36:37], v[36:37], v[36:37] op_sel:[0,1] op_sel_hi:[1,0]
	v_mov_b32_e32 v35, v42
	v_mov_b32_e32 v37, v43
	v_pk_add_f32 v[34:35], v[34:35], v[36:37]
	v_mul_f32_e32 v36, v73, v73
	v_mul_f32_e32 v42, v71, v71
	v_mul_f32_e32 v44, v150, v150
	v_mul_f32_e32 v45, v151, v151
	v_pk_fma_f32 v[36:37], v[72:73], v[72:73], v[36:37] op_sel_hi:[1,1,0]
	v_pk_fma_f32 v[42:43], v[70:71], v[70:71], v[42:43] op_sel_hi:[1,1,0]
	v_mov_b32_e32 v37, v44
	v_mov_b32_e32 v43, v45
	v_pk_add_f32 v[36:37], v[36:37], v[42:43]
	v_pk_mul_f32 v[42:43], v[154:155], v[154:155]
	v_pk_add_f32 v[34:35], v[34:35], v[36:37]
	v_pk_mul_f32 v[36:37], v[156:157], v[156:157]
	v_pk_add_f32 v[34:35], v[34:35], v[34:35] op_sel:[0,1] op_sel_hi:[1,0]
	v_pk_mov_b32 v[44:45], v[42:43], v[36:37] op_sel:[1,0]
	v_mov_b32_e32 v43, v37
	v_pk_add_f32 v[36:37], v[44:45], v[42:43]
	v_mul_f32_e32 v42, v40, v40
	v_mul_f32_e32 v43, v41, v41
	v_pk_add_f32 v[36:37], v[36:37], v[36:37] op_sel:[0,1] op_sel_hi:[1,0]
	v_mov_b32_e32 v35, v42
	v_mov_b32_e32 v37, v43
	v_pk_add_f32 v[34:35], v[34:35], v[36:37]
	v_mul_f32_e32 v36, v161, v161
	v_mul_f32_e32 v42, v159, v159
	v_mul_f32_e32 v44, v38, v38
	v_mul_f32_e32 v45, v39, v39
	v_pk_fma_f32 v[36:37], v[160:161], v[160:161], v[36:37] op_sel_hi:[1,1,0]
	v_pk_fma_f32 v[42:43], v[158:159], v[158:159], v[42:43] op_sel_hi:[1,1,0]
	v_mov_b32_e32 v37, v44
	v_mov_b32_e32 v43, v45
	v_pk_add_f32 v[36:37], v[36:37], v[42:43]
	s_nop 0
	v_pk_add_f32 v[34:35], v[34:35], v[36:37]
	s_nop 0
	v_add_f32_e32 v34, v34, v35
	ds_bpermute_b32 v35, v113, v34
	s_waitcnt lgkmcnt(0)
	v_add_f32_e32 v34, v34, v35
	ds_bpermute_b32 v35, v115, v34
	s_waitcnt lgkmcnt(0)
	v_add_f32_e32 v34, v34, v35
	ds_bpermute_b32 v35, v117, v34
	s_waitcnt lgkmcnt(0)
	v_add_f32_e32 v34, v34, v35
	ds_bpermute_b32 v35, v119, v34
	s_waitcnt lgkmcnt(0)
	v_add_f32_e32 v34, v34, v35
	v_fmamk_f32 v34, v34, 0x3b000000, v185
	v_cmp_gt_f32_e32 vcc, s66, v34
	v_mul_f32_e32 v35, 0x4b800000, v34
	s_nop 0
	v_cndmask_b32_e32 v34, v34, v35, vcc
	v_rsq_f32_e32 v34, v34
	s_nop 0
	v_mul_f32_e32 v35, 0x45800000, v34
	v_cndmask_b32_e32 v42, v34, v35, vcc
	global_load_dwordx4 v[34:37], v[98:99], off
	v_pk_mul_f32 v[44:45], v[148:149], v[42:43] op_sel_hi:[1,0]
	v_pk_mul_f32 v[46:47], v[146:147], v[42:43] op_sel_hi:[1,0]
	v_pk_mul_f32 v[48:49], v[62:63], v[42:43] op_sel_hi:[1,0]
	v_pk_mul_f32 v[40:41], v[40:41], v[42:43] op_sel_hi:[1,0]
	s_waitcnt vmcnt(0)
	v_pk_mul_f32 v[34:35], v[34:35], v[44:45]
	v_pk_mul_f32 v[36:37], v[36:37], v[46:47]
	v_cvt_pk_bf16_f32 v34, v34, v35
	s_nop 0
	v_cvt_pk_bf16_f32 v35, v36, v37
	v_pk_mul_f32 v[36:37], v[64:65], v[42:43] op_sel_hi:[1,0]
	v_pk_mul_f32 v[46:47], v[226:227], v[48:49]
	v_pk_mul_f32 v[36:37], v[224:225], v[36:37]
	v_lshl_add_u64 v[44:45], v[138:139], 0, s[24:25]
	v_cvt_pk_bf16_f32 v36, v36, v37
	v_cvt_pk_bf16_f32 v37, v46, v47
	v_pk_mul_f32 v[46:47], v[68:69], v[42:43] op_sel_hi:[1,0]
	v_permlane16_swap_b32_e32 v34, v36
	v_permlane16_swap_b32_e32 v35, v37
	global_store_dwordx4 v[44:45], v[34:37], off
	s_nop 0
	v_pk_mul_f32 v[44:45], v[66:67], v[42:43] op_sel_hi:[1,0]
	v_pk_mul_f32 v[48:49], v[70:71], v[42:43] op_sel_hi:[1,0]
	v_pk_mul_f32 v[34:35], v[228:229], v[44:45]
	v_pk_mul_f32 v[36:37], v[230:231], v[46:47]
	v_cvt_pk_bf16_f32 v34, v34, v35
	s_nop 0
	v_cvt_pk_bf16_f32 v35, v36, v37
	v_pk_mul_f32 v[36:37], v[72:73], v[42:43] op_sel_hi:[1,0]
	v_pk_mul_f32 v[46:47], v[234:235], v[48:49]
	v_pk_mul_f32 v[36:37], v[232:233], v[36:37]
	v_lshl_add_u64 v[44:45], v[140:141], 0, s[24:25]
	v_cvt_pk_bf16_f32 v36, v36, v37
	v_cvt_pk_bf16_f32 v37, v46, v47
	v_pk_mul_f32 v[46:47], v[150:151], v[42:43] op_sel_hi:[1,0]
	v_permlane16_swap_b32_e32 v34, v36
	v_permlane16_swap_b32_e32 v35, v37
	global_store_dwordx4 v[44:45], v[34:37], off
	s_nop 0
	v_pk_mul_f32 v[44:45], v[152:153], v[42:43] op_sel_hi:[1,0]
	v_pk_mul_f32 v[48:49], v[156:157], v[42:43] op_sel_hi:[1,0]
	v_pk_mul_f32 v[34:35], v[44:45], v[236:237]
	v_pk_mul_f32 v[36:37], v[46:47], v[238:239]
	v_cvt_pk_bf16_f32 v34, v34, v35
	s_nop 0
	v_cvt_pk_bf16_f32 v35, v36, v37
	v_pk_mul_f32 v[36:37], v[154:155], v[42:43] op_sel_hi:[1,0]
	v_pk_mul_f32 v[46:47], v[48:49], v[242:243]
	v_pk_mul_f32 v[36:37], v[36:37], v[240:241]
	v_lshl_add_u64 v[44:45], v[142:143], 0, s[24:25]
	v_cvt_pk_bf16_f32 v36, v36, v37
	v_cvt_pk_bf16_f32 v37, v46, v47
	v_pk_mul_f32 v[46:47], v[158:159], v[42:43] op_sel_hi:[1,0]
	v_permlane16_swap_b32_e32 v34, v36
	v_permlane16_swap_b32_e32 v35, v37
	global_store_dwordx4 v[44:45], v[34:37], off
	s_nop 0
	v_pk_mul_f32 v[44:45], v[160:161], v[42:43] op_sel_hi:[1,0]
	v_pk_mul_f32 v[42:43], v[38:39], v[42:43] op_sel_hi:[1,0]
	v_pk_mul_f32 v[36:37], v[46:47], v[246:247]
	v_pk_mul_f32 v[34:35], v[44:45], v[244:245]
	s_nop 0
	v_cvt_pk_bf16_f32 v34, v34, v35
	v_cvt_pk_bf16_f32 v35, v36, v37
	v_pk_mul_f32 v[38:39], v[42:43], v[250:251]
	v_pk_mul_f32 v[36:37], v[40:41], v[248:249]
	s_nop 0
	v_cvt_pk_bf16_f32 v36, v36, v37
	v_cvt_pk_bf16_f32 v37, v38, v39
	v_lshl_add_u64 v[38:39], v[144:145], 0, s[24:25]
	s_add_u32 s24, s24, 0x2000
	s_addc_u32 s25, s25, 0
	v_permlane16_swap_b32_e32 v34, v36
	v_permlane16_swap_b32_e32 v35, v37
	s_cmpk_eq_i32 s24, 0x4000
	global_store_dwordx4 v[38:39], v[34:37], off
	s_cbranch_scc0 .LBB0_414
	s_mov_b64 s[0:1], 0
